# GEMM phase tails: removed the vmcnt(0) drain before the LDS-free barrier (epilogues already retire the DMA loads)
# baseline (speedup 1.0000x reference)
.LBB0_362:
	v_readlane_b32 s76, v252, 46
	s_mov_b32 s77, 0x20000
	s_barrier

.LBB0_713:
	v_xor_b32_e32 v140, 16, v230
	v_xor_b32_e32 v141, 32, v230
	v_lshlrev_b32_e32 v140, 2, v140
	v_lshlrev_b32_e32 v141, 2, v141
	s_mov_b64 s[100:101], s[46:47]
	s_waitcnt vmcnt(14)
	v_lshlrev_b32_e32 v142, 16, v148
	v_and_b32_e32 v143, 0xffff0000, v148
	v_pk_add_f32 v[124:125], v[124:125], v[142:143]
	v_pk_mul_f32 v[222:223], v[124:125], v[124:125]
	v_cvt_pk_bf16_f32 v148, v124, v125
	v_lshlrev_b32_e32 v142, 16, v149
	v_and_b32_e32 v143, 0xffff0000, v149
	v_pk_add_f32 v[126:127], v[126:127], v[142:143]
	v_pk_fma_f32 v[222:223], v[126:127], v[126:127], v[222:223]
	v_cvt_pk_bf16_f32 v149, v126, v127
	v_lshlrev_b32_e32 v142, 16, v150
	v_and_b32_e32 v143, 0xffff0000, v150
	v_pk_add_f32 v[120:121], v[120:121], v[142:143]
	v_pk_fma_f32 v[222:223], v[120:121], v[120:121], v[222:223]
	v_cvt_pk_bf16_f32 v150, v120, v121
	v_lshlrev_b32_e32 v142, 16, v151
	v_and_b32_e32 v143, 0xffff0000, v151
	v_pk_add_f32 v[122:123], v[122:123], v[142:143]
	v_pk_fma_f32 v[222:223], v[122:123], v[122:123], v[222:223]
	v_cvt_pk_bf16_f32 v151, v122, v123
	global_store_dwordx4 v138, v[148:151], s[100:101]
	v_lshlrev_b32_e32 v142, 16, v152
	v_and_b32_e32 v143, 0xffff0000, v152
	v_pk_add_f32 v[116:117], v[116:117], v[142:143]
	v_pk_fma_f32 v[222:223], v[116:117], v[116:117], v[222:223]
	v_cvt_pk_bf16_f32 v152, v116, v117
	v_lshlrev_b32_e32 v142, 16, v153
	v_and_b32_e32 v143, 0xffff0000, v153
	v_pk_add_f32 v[118:119], v[118:119], v[142:143]
	v_pk_fma_f32 v[222:223], v[118:119], v[118:119], v[222:223]
	v_cvt_pk_bf16_f32 v153, v118, v119
	v_lshlrev_b32_e32 v142, 16, v154
	v_and_b32_e32 v143, 0xffff0000, v154
	v_pk_add_f32 v[112:113], v[112:113], v[142:143]
	v_pk_fma_f32 v[222:223], v[112:113], v[112:113], v[222:223]
	v_cvt_pk_bf16_f32 v154, v112, v113
	v_lshlrev_b32_e32 v142, 16, v155
	v_and_b32_e32 v143, 0xffff0000, v155
	v_pk_add_f32 v[114:115], v[114:115], v[142:143]
	v_pk_fma_f32 v[222:223], v[114:115], v[114:115], v[222:223]
	v_cvt_pk_bf16_f32 v155, v114, v115
	global_store_dwordx4 v138, v[152:155], s[100:101] offset:256
	v_add_f32_e32 v124, v222, v223
	s_add_u32 s100, s100, 0x8000
	s_addc_u32 s101, s101, 0
	s_waitcnt vmcnt(14)
	v_lshlrev_b32_e32 v142, 16, v156
	v_and_b32_e32 v143, 0xffff0000, v156
	v_pk_add_f32 v[108:109], v[108:109], v[142:143]
	v_pk_mul_f32 v[222:223], v[108:109], v[108:109]
	v_cvt_pk_bf16_f32 v156, v108, v109
	v_lshlrev_b32_e32 v142, 16, v157
	v_and_b32_e32 v143, 0xffff0000, v157
	v_pk_add_f32 v[110:111], v[110:111], v[142:143]
	v_pk_fma_f32 v[222:223], v[110:111], v[110:111], v[222:223]
	v_cvt_pk_bf16_f32 v157, v110, v111
	v_lshlrev_b32_e32 v142, 16, v158
	v_and_b32_e32 v143, 0xffff0000, v158
	v_pk_add_f32 v[104:105], v[104:105], v[142:143]
	v_pk_fma_f32 v[222:223], v[104:105], v[104:105], v[222:223]
	v_cvt_pk_bf16_f32 v158, v104, v105
	v_lshlrev_b32_e32 v142, 16, v159
	v_and_b32_e32 v143, 0xffff0000, v159
	v_pk_add_f32 v[106:107], v[106:107], v[142:143]
	v_pk_fma_f32 v[222:223], v[106:107], v[106:107], v[222:223]
	v_cvt_pk_bf16_f32 v159, v106, v107
	global_store_dwordx4 v138, v[156:159], s[100:101]
	v_lshlrev_b32_e32 v142, 16, v160
	v_and_b32_e32 v143, 0xffff0000, v160
	v_pk_add_f32 v[100:101], v[100:101], v[142:143]
	v_pk_fma_f32 v[222:223], v[100:101], v[100:101], v[222:223]
	v_cvt_pk_bf16_f32 v160, v100, v101
	v_lshlrev_b32_e32 v142, 16, v161
	v_and_b32_e32 v143, 0xffff0000, v161
	v_pk_add_f32 v[102:103], v[102:103], v[142:143]
	v_pk_fma_f32 v[222:223], v[102:103], v[102:103], v[222:223]
	v_cvt_pk_bf16_f32 v161, v102, v103
	v_lshlrev_b32_e32 v142, 16, v162
	v_and_b32_e32 v143, 0xffff0000, v162
	v_pk_add_f32 v[96:97], v[96:97], v[142:143]
	v_pk_fma_f32 v[222:223], v[96:97], v[96:97], v[222:223]
	v_cvt_pk_bf16_f32 v162, v96, v97
	v_lshlrev_b32_e32 v142, 16, v163
	v_and_b32_e32 v143, 0xffff0000, v163
	v_pk_add_f32 v[98:99], v[98:99], v[142:143]
	v_pk_fma_f32 v[222:223], v[98:99], v[98:99], v[222:223]
	v_cvt_pk_bf16_f32 v163, v98, v99
	global_store_dwordx4 v138, v[160:163], s[100:101] offset:256
	v_add_f32_e32 v108, v222, v223
	s_add_u32 s100, s100, 0x8000
	s_addc_u32 s101, s101, 0
	s_waitcnt vmcnt(14)
	v_lshlrev_b32_e32 v142, 16, v164
	v_and_b32_e32 v143, 0xffff0000, v164
	v_pk_add_f32 v[92:93], v[92:93], v[142:143]
	v_pk_mul_f32 v[222:223], v[92:93], v[92:93]
	v_cvt_pk_bf16_f32 v164, v92, v93
	v_lshlrev_b32_e32 v142, 16, v165
	v_and_b32_e32 v143, 0xffff0000, v165
	v_pk_add_f32 v[94:95], v[94:95], v[142:143]
	v_pk_fma_f32 v[222:223], v[94:95], v[94:95], v[222:223]
	v_cvt_pk_bf16_f32 v165, v94, v95
	v_lshlrev_b32_e32 v142, 16, v166
	v_and_b32_e32 v143, 0xffff0000, v166
	v_pk_add_f32 v[88:89], v[88:89], v[142:143]
	v_pk_fma_f32 v[222:223], v[88:89], v[88:89], v[222:223]
	v_cvt_pk_bf16_f32 v166, v88, v89
	v_lshlrev_b32_e32 v142, 16, v167
	v_and_b32_e32 v143, 0xffff0000, v167
	v_pk_add_f32 v[90:91], v[90:91], v[142:143]
	v_pk_fma_f32 v[222:223], v[90:91], v[90:91], v[222:223]
	v_cvt_pk_bf16_f32 v167, v90, v91
	global_store_dwordx4 v138, v[164:167], s[100:101]
	v_lshlrev_b32_e32 v142, 16, v168
	v_and_b32_e32 v143, 0xffff0000, v168
	v_pk_add_f32 v[84:85], v[84:85], v[142:143]
	v_pk_fma_f32 v[222:223], v[84:85], v[84:85], v[222:223]
	v_cvt_pk_bf16_f32 v168, v84, v85
	v_lshlrev_b32_e32 v142, 16, v169
	v_and_b32_e32 v143, 0xffff0000, v169
	v_pk_add_f32 v[86:87], v[86:87], v[142:143]
	v_pk_fma_f32 v[222:223], v[86:87], v[86:87], v[222:223]
	v_cvt_pk_bf16_f32 v169, v86, v87
	v_lshlrev_b32_e32 v142, 16, v170
	v_and_b32_e32 v143, 0xffff0000, v170
	v_pk_add_f32 v[80:81], v[80:81], v[142:143]
	v_pk_fma_f32 v[222:223], v[80:81], v[80:81], v[222:223]
	v_cvt_pk_bf16_f32 v170, v80, v81
	v_lshlrev_b32_e32 v142, 16, v171
	v_and_b32_e32 v143, 0xffff0000, v171
	v_pk_add_f32 v[82:83], v[82:83], v[142:143]
	v_pk_fma_f32 v[222:223], v[82:83], v[82:83], v[222:223]
	v_cvt_pk_bf16_f32 v171, v82, v83
	global_store_dwordx4 v138, v[168:171], s[100:101] offset:256
	v_add_f32_e32 v92, v222, v223
	s_add_u32 s100, s100, 0x8000
	s_addc_u32 s101, s101, 0
	s_waitcnt vmcnt(14)
	v_lshlrev_b32_e32 v142, 16, v172
	v_and_b32_e32 v143, 0xffff0000, v172
	v_pk_add_f32 v[76:77], v[76:77], v[142:143]
	v_pk_mul_f32 v[222:223], v[76:77], v[76:77]
	v_cvt_pk_bf16_f32 v172, v76, v77
	v_lshlrev_b32_e32 v142, 16, v173
	v_and_b32_e32 v143, 0xffff0000, v173
	v_pk_add_f32 v[78:79], v[78:79], v[142:143]
	v_pk_fma_f32 v[222:223], v[78:79], v[78:79], v[222:223]
	v_cvt_pk_bf16_f32 v173, v78, v79
	v_lshlrev_b32_e32 v142, 16, v174
	v_and_b32_e32 v143, 0xffff0000, v174
	v_pk_add_f32 v[72:73], v[72:73], v[142:143]
	v_pk_fma_f32 v[222:223], v[72:73], v[72:73], v[222:223]
	v_cvt_pk_bf16_f32 v174, v72, v73
	v_lshlrev_b32_e32 v142, 16, v175
	v_and_b32_e32 v143, 0xffff0000, v175
	v_pk_add_f32 v[74:75], v[74:75], v[142:143]
	v_pk_fma_f32 v[222:223], v[74:75], v[74:75], v[222:223]
	v_cvt_pk_bf16_f32 v175, v74, v75
	global_store_dwordx4 v138, v[172:175], s[100:101]
	v_lshlrev_b32_e32 v142, 16, v176
	v_and_b32_e32 v143, 0xffff0000, v176
	v_pk_add_f32 v[68:69], v[68:69], v[142:143]
	v_pk_fma_f32 v[222:223], v[68:69], v[68:69], v[222:223]
	v_cvt_pk_bf16_f32 v176, v68, v69
	v_lshlrev_b32_e32 v142, 16, v177
	v_and_b32_e32 v143, 0xffff0000, v177
	v_pk_add_f32 v[70:71], v[70:71], v[142:143]
	v_pk_fma_f32 v[222:223], v[70:71], v[70:71], v[222:223]
	v_cvt_pk_bf16_f32 v177, v70, v71
	v_lshlrev_b32_e32 v142, 16, v178
	v_and_b32_e32 v143, 0xffff0000, v178
	v_pk_add_f32 v[64:65], v[64:65], v[142:143]
	v_pk_fma_f32 v[222:223], v[64:65], v[64:65], v[222:223]
	v_cvt_pk_bf16_f32 v178, v64, v65
	v_lshlrev_b32_e32 v142, 16, v179
	v_and_b32_e32 v143, 0xffff0000, v179
	v_pk_add_f32 v[66:67], v[66:67], v[142:143]
	v_pk_fma_f32 v[222:223], v[66:67], v[66:67], v[222:223]
	v_cvt_pk_bf16_f32 v179, v66, v67
	global_store_dwordx4 v138, v[176:179], s[100:101] offset:256
	v_add_f32_e32 v76, v222, v223
	s_add_u32 s100, s100, 0x28000
	s_addc_u32 s101, s101, 0
	s_waitcnt vmcnt(14)
	v_lshlrev_b32_e32 v142, 16, v180
	v_and_b32_e32 v143, 0xffff0000, v180
	v_pk_add_f32 v[60:61], v[60:61], v[142:143]
	v_pk_mul_f32 v[222:223], v[60:61], v[60:61]
	v_cvt_pk_bf16_f32 v180, v60, v61
	v_lshlrev_b32_e32 v142, 16, v181
	v_and_b32_e32 v143, 0xffff0000, v181
	v_pk_add_f32 v[62:63], v[62:63], v[142:143]
	v_pk_fma_f32 v[222:223], v[62:63], v[62:63], v[222:223]
	v_cvt_pk_bf16_f32 v181, v62, v63
	v_lshlrev_b32_e32 v142, 16, v182
	v_and_b32_e32 v143, 0xffff0000, v182
	v_pk_add_f32 v[56:57], v[56:57], v[142:143]
	v_pk_fma_f32 v[222:223], v[56:57], v[56:57], v[222:223]
	v_cvt_pk_bf16_f32 v182, v56, v57
	v_lshlrev_b32_e32 v142, 16, v183
	v_and_b32_e32 v143, 0xffff0000, v183
	v_pk_add_f32 v[58:59], v[58:59], v[142:143]
	v_pk_fma_f32 v[222:223], v[58:59], v[58:59], v[222:223]
	v_cvt_pk_bf16_f32 v183, v58, v59
	global_store_dwordx4 v138, v[180:183], s[100:101]
	v_lshlrev_b32_e32 v142, 16, v184
	v_and_b32_e32 v143, 0xffff0000, v184
	v_pk_add_f32 v[52:53], v[52:53], v[142:143]
	v_pk_fma_f32 v[222:223], v[52:53], v[52:53], v[222:223]
	v_cvt_pk_bf16_f32 v184, v52, v53
	v_lshlrev_b32_e32 v142, 16, v185
	v_and_b32_e32 v143, 0xffff0000, v185
	v_pk_add_f32 v[54:55], v[54:55], v[142:143]
	v_pk_fma_f32 v[222:223], v[54:55], v[54:55], v[222:223]
	v_cvt_pk_bf16_f32 v185, v54, v55
	v_lshlrev_b32_e32 v142, 16, v186
	v_and_b32_e32 v143, 0xffff0000, v186
	v_pk_add_f32 v[48:49], v[48:49], v[142:143]
	v_pk_fma_f32 v[222:223], v[48:49], v[48:49], v[222:223]
	v_cvt_pk_bf16_f32 v186, v48, v49
	v_lshlrev_b32_e32 v142, 16, v187
	v_and_b32_e32 v143, 0xffff0000, v187
	v_pk_add_f32 v[50:51], v[50:51], v[142:143]
	v_pk_fma_f32 v[222:223], v[50:51], v[50:51], v[222:223]
	v_cvt_pk_bf16_f32 v187, v50, v51
	global_store_dwordx4 v138, v[184:187], s[100:101] offset:256
	v_add_f32_e32 v60, v222, v223
	s_add_u32 s100, s100, 0x8000
	s_addc_u32 s101, s101, 0
	s_waitcnt vmcnt(14)
	v_lshlrev_b32_e32 v142, 16, v188
	v_and_b32_e32 v143, 0xffff0000, v188
	v_pk_add_f32 v[44:45], v[44:45], v[142:143]
	v_pk_mul_f32 v[222:223], v[44:45], v[44:45]
	v_cvt_pk_bf16_f32 v188, v44, v45
	v_lshlrev_b32_e32 v142, 16, v189
	v_and_b32_e32 v143, 0xffff0000, v189
	v_pk_add_f32 v[46:47], v[46:47], v[142:143]
	v_pk_fma_f32 v[222:223], v[46:47], v[46:47], v[222:223]
	v_cvt_pk_bf16_f32 v189, v46, v47
	v_lshlrev_b32_e32 v142, 16, v190
	v_and_b32_e32 v143, 0xffff0000, v190
	v_pk_add_f32 v[40:41], v[40:41], v[142:143]
	v_pk_fma_f32 v[222:223], v[40:41], v[40:41], v[222:223]
	v_cvt_pk_bf16_f32 v190, v40, v41
	v_lshlrev_b32_e32 v142, 16, v191
	v_and_b32_e32 v143, 0xffff0000, v191
	v_pk_add_f32 v[42:43], v[42:43], v[142:143]
	v_pk_fma_f32 v[222:223], v[42:43], v[42:43], v[222:223]
	v_cvt_pk_bf16_f32 v191, v42, v43
	global_store_dwordx4 v138, v[188:191], s[100:101]
	v_lshlrev_b32_e32 v142, 16, v192
	v_and_b32_e32 v143, 0xffff0000, v192
	v_pk_add_f32 v[36:37], v[36:37], v[142:143]
	v_pk_fma_f32 v[222:223], v[36:37], v[36:37], v[222:223]
	v_cvt_pk_bf16_f32 v192, v36, v37
	v_lshlrev_b32_e32 v142, 16, v193
	v_and_b32_e32 v143, 0xffff0000, v193
	v_pk_add_f32 v[38:39], v[38:39], v[142:143]
	v_pk_fma_f32 v[222:223], v[38:39], v[38:39], v[222:223]
	v_cvt_pk_bf16_f32 v193, v38, v39
	v_lshlrev_b32_e32 v142, 16, v194
	v_and_b32_e32 v143, 0xffff0000, v194
	v_pk_add_f32 v[32:33], v[32:33], v[142:143]
	v_pk_fma_f32 v[222:223], v[32:33], v[32:33], v[222:223]
	v_cvt_pk_bf16_f32 v194, v32, v33
	v_lshlrev_b32_e32 v142, 16, v195
	v_and_b32_e32 v143, 0xffff0000, v195
	v_pk_add_f32 v[34:35], v[34:35], v[142:143]
	v_pk_fma_f32 v[222:223], v[34:35], v[34:35], v[222:223]
	v_cvt_pk_bf16_f32 v195, v34, v35
	global_store_dwordx4 v138, v[192:195], s[100:101] offset:256
	v_add_f32_e32 v44, v222, v223
	s_add_u32 s100, s100, 0x8000
	s_addc_u32 s101, s101, 0
	s_waitcnt vmcnt(14)
	v_lshlrev_b32_e32 v142, 16, v196
	v_and_b32_e32 v143, 0xffff0000, v196
	v_pk_add_f32 v[28:29], v[28:29], v[142:143]
	v_pk_mul_f32 v[222:223], v[28:29], v[28:29]
	v_cvt_pk_bf16_f32 v196, v28, v29
	v_lshlrev_b32_e32 v142, 16, v197
	v_and_b32_e32 v143, 0xffff0000, v197
	v_pk_add_f32 v[30:31], v[30:31], v[142:143]
	v_pk_fma_f32 v[222:223], v[30:31], v[30:31], v[222:223]
	v_cvt_pk_bf16_f32 v197, v30, v31
	v_lshlrev_b32_e32 v142, 16, v198
	v_and_b32_e32 v143, 0xffff0000, v198
	v_pk_add_f32 v[24:25], v[24:25], v[142:143]
	v_pk_fma_f32 v[222:223], v[24:25], v[24:25], v[222:223]
	v_cvt_pk_bf16_f32 v198, v24, v25
	v_lshlrev_b32_e32 v142, 16, v199
	v_and_b32_e32 v143, 0xffff0000, v199
	v_pk_add_f32 v[26:27], v[26:27], v[142:143]
	v_pk_fma_f32 v[222:223], v[26:27], v[26:27], v[222:223]
	v_cvt_pk_bf16_f32 v199, v26, v27
	global_store_dwordx4 v138, v[196:199], s[100:101]
	v_lshlrev_b32_e32 v142, 16, v200
	v_and_b32_e32 v143, 0xffff0000, v200
	v_pk_add_f32 v[20:21], v[20:21], v[142:143]
	v_pk_fma_f32 v[222:223], v[20:21], v[20:21], v[222:223]
	v_cvt_pk_bf16_f32 v200, v20, v21
	v_lshlrev_b32_e32 v142, 16, v201
	v_and_b32_e32 v143, 0xffff0000, v201
	v_pk_add_f32 v[22:23], v[22:23], v[142:143]
	v_pk_fma_f32 v[222:223], v[22:23], v[22:23], v[222:223]
	v_cvt_pk_bf16_f32 v201, v22, v23
	v_lshlrev_b32_e32 v142, 16, v202
	v_and_b32_e32 v143, 0xffff0000, v202
	v_pk_add_f32 v[16:17], v[16:17], v[142:143]
	v_pk_fma_f32 v[222:223], v[16:17], v[16:17], v[222:223]
	v_cvt_pk_bf16_f32 v202, v16, v17
	v_lshlrev_b32_e32 v142, 16, v203
	v_and_b32_e32 v143, 0xffff0000, v203
	v_pk_add_f32 v[18:19], v[18:19], v[142:143]
	v_pk_fma_f32 v[222:223], v[18:19], v[18:19], v[222:223]
	v_cvt_pk_bf16_f32 v203, v18, v19
	global_store_dwordx4 v138, v[200:203], s[100:101] offset:256
	v_add_f32_e32 v28, v222, v223
	s_add_u32 s100, s100, 0x8000
	s_addc_u32 s101, s101, 0
	s_waitcnt vmcnt(14)
	v_lshlrev_b32_e32 v142, 16, v204
	v_and_b32_e32 v143, 0xffff0000, v204
	v_pk_add_f32 v[12:13], v[12:13], v[142:143]
	v_pk_mul_f32 v[222:223], v[12:13], v[12:13]
	v_cvt_pk_bf16_f32 v204, v12, v13
	v_lshlrev_b32_e32 v142, 16, v205
	v_and_b32_e32 v143, 0xffff0000, v205
	v_pk_add_f32 v[14:15], v[14:15], v[142:143]
	v_pk_fma_f32 v[222:223], v[14:15], v[14:15], v[222:223]
	v_cvt_pk_bf16_f32 v205, v14, v15
	v_lshlrev_b32_e32 v142, 16, v206
	v_and_b32_e32 v143, 0xffff0000, v206
	v_pk_add_f32 v[8:9], v[8:9], v[142:143]
	v_pk_fma_f32 v[222:223], v[8:9], v[8:9], v[222:223]
	v_cvt_pk_bf16_f32 v206, v8, v9
	v_lshlrev_b32_e32 v142, 16, v207
	v_and_b32_e32 v143, 0xffff0000, v207
	v_pk_add_f32 v[10:11], v[10:11], v[142:143]
	v_pk_fma_f32 v[222:223], v[10:11], v[10:11], v[222:223]
	v_cvt_pk_bf16_f32 v207, v10, v11
	global_store_dwordx4 v138, v[204:207], s[100:101]
	v_lshlrev_b32_e32 v142, 16, v236
	v_and_b32_e32 v143, 0xffff0000, v236
	v_pk_add_f32 v[4:5], v[4:5], v[142:143]
	v_pk_fma_f32 v[222:223], v[4:5], v[4:5], v[222:223]
	v_cvt_pk_bf16_f32 v236, v4, v5
	v_lshlrev_b32_e32 v142, 16, v237
	v_and_b32_e32 v143, 0xffff0000, v237
	v_pk_add_f32 v[6:7], v[6:7], v[142:143]
	v_pk_fma_f32 v[222:223], v[6:7], v[6:7], v[222:223]
	v_cvt_pk_bf16_f32 v237, v6, v7
	v_lshlrev_b32_e32 v142, 16, v238
	v_and_b32_e32 v143, 0xffff0000, v238
	v_pk_add_f32 v[0:1], v[0:1], v[142:143]
	v_pk_fma_f32 v[222:223], v[0:1], v[0:1], v[222:223]
	v_cvt_pk_bf16_f32 v238, v0, v1
	v_lshlrev_b32_e32 v142, 16, v239
	v_and_b32_e32 v143, 0xffff0000, v239
	v_pk_add_f32 v[2:3], v[2:3], v[142:143]
	v_pk_fma_f32 v[222:223], v[2:3], v[2:3], v[222:223]
	v_cvt_pk_bf16_f32 v239, v2, v3
	global_store_dwordx4 v138, v[236:239], s[100:101] offset:256
	v_add_f32_e32 v12, v222, v223
	ds_bpermute_b32 v125, v140, v124
	ds_bpermute_b32 v109, v140, v108
	ds_bpermute_b32 v93, v140, v92
	ds_bpermute_b32 v77, v140, v76
	ds_bpermute_b32 v61, v140, v60
	ds_bpermute_b32 v45, v140, v44
	ds_bpermute_b32 v29, v140, v28
	ds_bpermute_b32 v13, v140, v12
	s_waitcnt lgkmcnt(0)
	v_add_f32_e32 v124, v124, v125
	v_add_f32_e32 v108, v108, v109
	v_add_f32_e32 v92, v92, v93
	v_add_f32_e32 v76, v76, v77
	v_add_f32_e32 v60, v60, v61
	v_add_f32_e32 v44, v44, v45
	v_add_f32_e32 v28, v28, v29
	v_add_f32_e32 v12, v12, v13
	ds_bpermute_b32 v125, v141, v124
	ds_bpermute_b32 v109, v141, v108
	ds_bpermute_b32 v93, v141, v92
	ds_bpermute_b32 v77, v141, v76
	ds_bpermute_b32 v61, v141, v60
	ds_bpermute_b32 v45, v141, v44
	ds_bpermute_b32 v29, v141, v28
	ds_bpermute_b32 v13, v141, v12
	s_waitcnt lgkmcnt(0)
	v_add_f32_e32 v124, v124, v125
	v_add_f32_e32 v108, v108, v109
	v_add_f32_e32 v92, v92, v93
	v_add_f32_e32 v76, v76, v77
	v_add_f32_e32 v60, v60, v61
	v_add_f32_e32 v44, v44, v45
	v_add_f32_e32 v28, v28, v29
	v_add_f32_e32 v12, v12, v13
	s_and_saveexec_b64 s[98:99], s[4:5]
	global_atomic_add_f32 v139, v124, s[76:77]
	global_atomic_add_f32 v139, v108, s[76:77] offset:64
	global_atomic_add_f32 v139, v92, s[76:77] offset:128
	global_atomic_add_f32 v139, v76, s[76:77] offset:192
	global_atomic_add_f32 v139, v60, s[76:77] offset:512
	global_atomic_add_f32 v139, v44, s[76:77] offset:576
	global_atomic_add_f32 v139, v28, s[76:77] offset:640
	global_atomic_add_f32 v139, v12, s[76:77] offset:704
	s_or_b64 exec, exec, s[98:99]
	s_andn2_b64 vcc, exec, s[6:7]
	s_mov_b64 s[6:7], -1
	s_cbranch_vccnz .LBB0_702
	s_andn2_b64 vcc, exec, s[0:1]
	s_cbranch_vccnz .LBB0_701
	s_barrier
	s_branch .LBB0_701
.LBB0_732:
	s_barrier
.LBB0_733:
	v_readlane_b32 s0, v252, 50
	v_mov_b32_e32 v4, v226
	v_readlane_b32 s1, v252, 51
	s_and_b64 vcc, exec, s[0:1]
	v_readfirstlane_b32 s0, v4
	s_cbranch_vccnz .LBB0_738
	s_ashr_i32 s0, s0, 6
	s_mul_i32 s1, s0, 0x2400
	s_lshl_b32 s0, s0, 7
	s_add_i32 s6, s1, 0
	s_ashr_i32 s1, s0, 31
	s_lshl_b64 s[0:1], s[0:1], 1
	s_add_u32 s4, s86, s0
	s_addc_u32 s5, s87, s1
	v_and_b32_e32 v6, 7, v4
	s_add_u32 s0, s28, s0
	v_lshlrev_b32_e32 v208, 4, v6
	s_addc_u32 s1, s29, s1
	v_and_b32_e32 v5, 15, v4
	v_bfe_u32 v8, v4, 3, 3
	v_lshl_add_u64 v[2:3], s[0:1], 0, v[208:209]
	v_mov_b32_e32 v9, s6
	s_movk_i32 s0, 0x90
	v_mul_u32_u24_e32 v7, 0x90, v5
	v_and_b32_e32 v12, 48, v4
	v_mad_u32_u24 v11, v8, s0, v9
	v_mad_u32_u24 v5, v5, s0, v9
	v_ashrrev_i32_e32 v9, 3, v4
	v_add_u32_e32 v13, s6, v12
	v_lshlrev_b32_e32 v4, 2, v6
	v_mul_lo_u32 v10, v9, s0
	s_waitcnt lgkmcnt(0)
	v_lshl_add_u64 v[0:1], s[4:5], 0, v[208:209]
	v_add3_u32 v10, 0, v10, v208
	v_cmp_eq_u32_e64 s[0:1], 0, v6
	v_add_u32_e32 v11, v11, v208
	v_add_u32_e32 v12, v5, v12
	v_add_u32_e32 v13, v13, v7
	v_lshlrev_b32_e32 v4, 1, v4
	v_readlane_b32 s6, v252, 41
	v_readlane_b32 s7, v252, 43
	s_mov_b32 s12, s2
	s_branch .LBB0_736

.LBB0_798:
	s_mov_b64 s[20:21], -1
	v_lshlrev_b32_e32 v138, 13, v140
	v_lshl_add_u32 v138, v142, 1, v138
	s_lshl_b32 s10, s40, 21
	s_lshl_b32 s11, s41, 9
	s_add_i32 s10, s10, s11
	s_add_u32 s100, s88, s10
	s_addc_u32 s101, s89, 0
	s_waitcnt vmcnt(0)
	v_fmamk_f32 v160, v160, 0x3a800000, v228
	v_fmamk_f32 v161, v161, 0x3a800000, v228
	v_fmamk_f32 v162, v162, 0x3a800000, v228
	v_fmamk_f32 v163, v163, 0x3a800000, v228
	v_fmamk_f32 v164, v164, 0x3a800000, v228
	v_fmamk_f32 v165, v165, 0x3a800000, v228
	v_fmamk_f32 v166, v166, 0x3a800000, v228
	v_fmamk_f32 v167, v167, 0x3a800000, v228
	v_rsq_f32_e32 v160, v160
	v_rsq_f32_e32 v161, v161
	v_rsq_f32_e32 v162, v162
	v_rsq_f32_e32 v163, v163
	v_rsq_f32_e32 v164, v164
	v_rsq_f32_e32 v165, v165
	v_rsq_f32_e32 v166, v166
	v_rsq_f32_e32 v167, v167
	v_pk_mul_f32 v[124:125], v[124:125], v[160:161] op_sel_hi:[1,0]
	v_pk_mul_f32 v[126:127], v[126:127], v[160:161] op_sel_hi:[1,0]
	v_pk_mul_f32 v[120:121], v[120:121], v[160:161] op_sel_hi:[1,0]
	v_pk_mul_f32 v[122:123], v[122:123], v[160:161] op_sel_hi:[1,0]
	v_pk_mul_f32 v[116:117], v[116:117], v[160:161] op_sel_hi:[1,0]
	v_pk_mul_f32 v[118:119], v[118:119], v[160:161] op_sel_hi:[1,0]
	v_pk_mul_f32 v[112:113], v[112:113], v[160:161] op_sel_hi:[1,0]
	v_pk_mul_f32 v[114:115], v[114:115], v[160:161] op_sel_hi:[1,0]
	v_max_f32_e32 v124, 0, v124
	v_max_f32_e32 v125, 0, v125
	v_max_f32_e32 v126, 0, v126
	v_max_f32_e32 v127, 0, v127
	v_max_f32_e32 v120, 0, v120
	v_max_f32_e32 v121, 0, v121
	v_max_f32_e32 v122, 0, v122
	v_max_f32_e32 v123, 0, v123
	v_max_f32_e32 v116, 0, v116
	v_max_f32_e32 v117, 0, v117
	v_max_f32_e32 v118, 0, v118
	v_max_f32_e32 v119, 0, v119
	v_max_f32_e32 v112, 0, v112
	v_max_f32_e32 v113, 0, v113
	v_max_f32_e32 v114, 0, v114
	v_max_f32_e32 v115, 0, v115
	v_pk_mul_f32 v[124:125], v[124:125], v[124:125]
	v_pk_mul_f32 v[126:127], v[126:127], v[126:127]
	v_pk_mul_f32 v[120:121], v[120:121], v[120:121]
	v_pk_mul_f32 v[122:123], v[122:123], v[122:123]
	v_pk_mul_f32 v[116:117], v[116:117], v[116:117]
	v_pk_mul_f32 v[118:119], v[118:119], v[118:119]
	v_pk_mul_f32 v[112:113], v[112:113], v[112:113]
	v_pk_mul_f32 v[114:115], v[114:115], v[114:115]
	v_cvt_pk_bf16_f32 v124, v124, v125
	v_cvt_pk_bf16_f32 v125, v126, v127
	v_cvt_pk_bf16_f32 v126, v120, v121
	v_cvt_pk_bf16_f32 v127, v122, v123
	global_store_dwordx4 v138, v[124:127], s[100:101]
	v_cvt_pk_bf16_f32 v116, v116, v117
	v_cvt_pk_bf16_f32 v117, v118, v119
	v_cvt_pk_bf16_f32 v118, v112, v113
	v_cvt_pk_bf16_f32 v119, v114, v115
	global_store_dwordx4 v138, v[116:119], s[100:101] offset:256
	s_add_u32 s100, s100, 0x20000
	s_addc_u32 s101, s101, 0
	v_pk_mul_f32 v[108:109], v[108:109], v[160:161] op_sel:[0,1] op_sel_hi:[1,1]
	v_pk_mul_f32 v[110:111], v[110:111], v[160:161] op_sel:[0,1] op_sel_hi:[1,1]
	v_pk_mul_f32 v[104:105], v[104:105], v[160:161] op_sel:[0,1] op_sel_hi:[1,1]
	v_pk_mul_f32 v[106:107], v[106:107], v[160:161] op_sel:[0,1] op_sel_hi:[1,1]
	v_pk_mul_f32 v[100:101], v[100:101], v[160:161] op_sel:[0,1] op_sel_hi:[1,1]
	v_pk_mul_f32 v[102:103], v[102:103], v[160:161] op_sel:[0,1] op_sel_hi:[1,1]
	v_pk_mul_f32 v[96:97], v[96:97], v[160:161] op_sel:[0,1] op_sel_hi:[1,1]
	v_pk_mul_f32 v[98:99], v[98:99], v[160:161] op_sel:[0,1] op_sel_hi:[1,1]
	v_max_f32_e32 v108, 0, v108
	v_max_f32_e32 v109, 0, v109
	v_max_f32_e32 v110, 0, v110
	v_max_f32_e32 v111, 0, v111
	v_max_f32_e32 v104, 0, v104
	v_max_f32_e32 v105, 0, v105
	v_max_f32_e32 v106, 0, v106
	v_max_f32_e32 v107, 0, v107
	v_max_f32_e32 v100, 0, v100
	v_max_f32_e32 v101, 0, v101
	v_max_f32_e32 v102, 0, v102
	v_max_f32_e32 v103, 0, v103
	v_max_f32_e32 v96, 0, v96
	v_max_f32_e32 v97, 0, v97
	v_max_f32_e32 v98, 0, v98
	v_max_f32_e32 v99, 0, v99
	v_pk_mul_f32 v[108:109], v[108:109], v[108:109]
	v_pk_mul_f32 v[110:111], v[110:111], v[110:111]
	v_pk_mul_f32 v[104:105], v[104:105], v[104:105]
	v_pk_mul_f32 v[106:107], v[106:107], v[106:107]
	v_pk_mul_f32 v[100:101], v[100:101], v[100:101]
	v_pk_mul_f32 v[102:103], v[102:103], v[102:103]
	v_pk_mul_f32 v[96:97], v[96:97], v[96:97]
	v_pk_mul_f32 v[98:99], v[98:99], v[98:99]
	v_cvt_pk_bf16_f32 v108, v108, v109
	v_cvt_pk_bf16_f32 v109, v110, v111
	v_cvt_pk_bf16_f32 v110, v104, v105
	v_cvt_pk_bf16_f32 v111, v106, v107
	global_store_dwordx4 v138, v[108:111], s[100:101]
	v_cvt_pk_bf16_f32 v100, v100, v101
	v_cvt_pk_bf16_f32 v101, v102, v103
	v_cvt_pk_bf16_f32 v102, v96, v97
	v_cvt_pk_bf16_f32 v103, v98, v99
	global_store_dwordx4 v138, v[100:103], s[100:101] offset:256
	s_add_u32 s100, s100, 0x20000
	s_addc_u32 s101, s101, 0
	v_pk_mul_f32 v[92:93], v[92:93], v[162:163] op_sel_hi:[1,0]
	v_pk_mul_f32 v[94:95], v[94:95], v[162:163] op_sel_hi:[1,0]
	v_pk_mul_f32 v[88:89], v[88:89], v[162:163] op_sel_hi:[1,0]
	v_pk_mul_f32 v[90:91], v[90:91], v[162:163] op_sel_hi:[1,0]
	v_pk_mul_f32 v[84:85], v[84:85], v[162:163] op_sel_hi:[1,0]
	v_pk_mul_f32 v[86:87], v[86:87], v[162:163] op_sel_hi:[1,0]
	v_pk_mul_f32 v[80:81], v[80:81], v[162:163] op_sel_hi:[1,0]
	v_pk_mul_f32 v[82:83], v[82:83], v[162:163] op_sel_hi:[1,0]
	v_max_f32_e32 v92, 0, v92
	v_max_f32_e32 v93, 0, v93
	v_max_f32_e32 v94, 0, v94
	v_max_f32_e32 v95, 0, v95
	v_max_f32_e32 v88, 0, v88
	v_max_f32_e32 v89, 0, v89
	v_max_f32_e32 v90, 0, v90
	v_max_f32_e32 v91, 0, v91
	v_max_f32_e32 v84, 0, v84
	v_max_f32_e32 v85, 0, v85
	v_max_f32_e32 v86, 0, v86
	v_max_f32_e32 v87, 0, v87
	v_max_f32_e32 v80, 0, v80
	v_max_f32_e32 v81, 0, v81
	v_max_f32_e32 v82, 0, v82
	v_max_f32_e32 v83, 0, v83
	v_pk_mul_f32 v[92:93], v[92:93], v[92:93]
	v_pk_mul_f32 v[94:95], v[94:95], v[94:95]
	v_pk_mul_f32 v[88:89], v[88:89], v[88:89]
	v_pk_mul_f32 v[90:91], v[90:91], v[90:91]
	v_pk_mul_f32 v[84:85], v[84:85], v[84:85]
	v_pk_mul_f32 v[86:87], v[86:87], v[86:87]
	v_pk_mul_f32 v[80:81], v[80:81], v[80:81]
	v_pk_mul_f32 v[82:83], v[82:83], v[82:83]
	v_cvt_pk_bf16_f32 v92, v92, v93
	v_cvt_pk_bf16_f32 v93, v94, v95
	v_cvt_pk_bf16_f32 v94, v88, v89
	v_cvt_pk_bf16_f32 v95, v90, v91
	global_store_dwordx4 v138, v[92:95], s[100:101]
	v_cvt_pk_bf16_f32 v84, v84, v85
	v_cvt_pk_bf16_f32 v85, v86, v87
	v_cvt_pk_bf16_f32 v86, v80, v81
	v_cvt_pk_bf16_f32 v87, v82, v83
	global_store_dwordx4 v138, v[84:87], s[100:101] offset:256
	s_add_u32 s100, s100, 0x20000
	s_addc_u32 s101, s101, 0
	v_pk_mul_f32 v[76:77], v[76:77], v[162:163] op_sel:[0,1] op_sel_hi:[1,1]
	v_pk_mul_f32 v[78:79], v[78:79], v[162:163] op_sel:[0,1] op_sel_hi:[1,1]
	v_pk_mul_f32 v[72:73], v[72:73], v[162:163] op_sel:[0,1] op_sel_hi:[1,1]
	v_pk_mul_f32 v[74:75], v[74:75], v[162:163] op_sel:[0,1] op_sel_hi:[1,1]
	v_pk_mul_f32 v[68:69], v[68:69], v[162:163] op_sel:[0,1] op_sel_hi:[1,1]
	v_pk_mul_f32 v[70:71], v[70:71], v[162:163] op_sel:[0,1] op_sel_hi:[1,1]
	v_pk_mul_f32 v[64:65], v[64:65], v[162:163] op_sel:[0,1] op_sel_hi:[1,1]
	v_pk_mul_f32 v[66:67], v[66:67], v[162:163] op_sel:[0,1] op_sel_hi:[1,1]
	v_max_f32_e32 v76, 0, v76
	v_max_f32_e32 v77, 0, v77
	v_max_f32_e32 v78, 0, v78
	v_max_f32_e32 v79, 0, v79
	v_max_f32_e32 v72, 0, v72
	v_max_f32_e32 v73, 0, v73
	v_max_f32_e32 v74, 0, v74
	v_max_f32_e32 v75, 0, v75
	v_max_f32_e32 v68, 0, v68
	v_max_f32_e32 v69, 0, v69
	v_max_f32_e32 v70, 0, v70
	v_max_f32_e32 v71, 0, v71
	v_max_f32_e32 v64, 0, v64
	v_max_f32_e32 v65, 0, v65
	v_max_f32_e32 v66, 0, v66
	v_max_f32_e32 v67, 0, v67
	v_pk_mul_f32 v[76:77], v[76:77], v[76:77]
	v_pk_mul_f32 v[78:79], v[78:79], v[78:79]
	v_pk_mul_f32 v[72:73], v[72:73], v[72:73]
	v_pk_mul_f32 v[74:75], v[74:75], v[74:75]
	v_pk_mul_f32 v[68:69], v[68:69], v[68:69]
	v_pk_mul_f32 v[70:71], v[70:71], v[70:71]
	v_pk_mul_f32 v[64:65], v[64:65], v[64:65]
	v_pk_mul_f32 v[66:67], v[66:67], v[66:67]
	v_cvt_pk_bf16_f32 v76, v76, v77
	v_cvt_pk_bf16_f32 v77, v78, v79
	v_cvt_pk_bf16_f32 v78, v72, v73
	v_cvt_pk_bf16_f32 v79, v74, v75
	global_store_dwordx4 v138, v[76:79], s[100:101]
	v_cvt_pk_bf16_f32 v68, v68, v69
	v_cvt_pk_bf16_f32 v69, v70, v71
	v_cvt_pk_bf16_f32 v70, v64, v65
	v_cvt_pk_bf16_f32 v71, v66, v67
	global_store_dwordx4 v138, v[68:71], s[100:101] offset:256
	s_add_u32 s100, s100, 0xa0000
	s_addc_u32 s101, s101, 0
	v_pk_mul_f32 v[60:61], v[60:61], v[164:165] op_sel_hi:[1,0]
	v_pk_mul_f32 v[62:63], v[62:63], v[164:165] op_sel_hi:[1,0]
	v_pk_mul_f32 v[56:57], v[56:57], v[164:165] op_sel_hi:[1,0]
	v_pk_mul_f32 v[58:59], v[58:59], v[164:165] op_sel_hi:[1,0]
	v_pk_mul_f32 v[52:53], v[52:53], v[164:165] op_sel_hi:[1,0]
	v_pk_mul_f32 v[54:55], v[54:55], v[164:165] op_sel_hi:[1,0]
	v_pk_mul_f32 v[48:49], v[48:49], v[164:165] op_sel_hi:[1,0]
	v_pk_mul_f32 v[50:51], v[50:51], v[164:165] op_sel_hi:[1,0]
	v_max_f32_e32 v60, 0, v60
	v_max_f32_e32 v61, 0, v61
	v_max_f32_e32 v62, 0, v62
	v_max_f32_e32 v63, 0, v63
	v_max_f32_e32 v56, 0, v56
	v_max_f32_e32 v57, 0, v57
	v_max_f32_e32 v58, 0, v58
	v_max_f32_e32 v59, 0, v59
	v_max_f32_e32 v52, 0, v52
	v_max_f32_e32 v53, 0, v53
	v_max_f32_e32 v54, 0, v54
	v_max_f32_e32 v55, 0, v55
	v_max_f32_e32 v48, 0, v48
	v_max_f32_e32 v49, 0, v49
	v_max_f32_e32 v50, 0, v50
	v_max_f32_e32 v51, 0, v51
	v_pk_mul_f32 v[60:61], v[60:61], v[60:61]
	v_pk_mul_f32 v[62:63], v[62:63], v[62:63]
	v_pk_mul_f32 v[56:57], v[56:57], v[56:57]
	v_pk_mul_f32 v[58:59], v[58:59], v[58:59]
	v_pk_mul_f32 v[52:53], v[52:53], v[52:53]
	v_pk_mul_f32 v[54:55], v[54:55], v[54:55]
	v_pk_mul_f32 v[48:49], v[48:49], v[48:49]
	v_pk_mul_f32 v[50:51], v[50:51], v[50:51]
	v_cvt_pk_bf16_f32 v60, v60, v61
	v_cvt_pk_bf16_f32 v61, v62, v63
	v_cvt_pk_bf16_f32 v62, v56, v57
	v_cvt_pk_bf16_f32 v63, v58, v59
	global_store_dwordx4 v138, v[60:63], s[100:101]
	v_cvt_pk_bf16_f32 v52, v52, v53
	v_cvt_pk_bf16_f32 v53, v54, v55
	v_cvt_pk_bf16_f32 v54, v48, v49
	v_cvt_pk_bf16_f32 v55, v50, v51
	global_store_dwordx4 v138, v[52:55], s[100:101] offset:256
	s_add_u32 s100, s100, 0x20000
	s_addc_u32 s101, s101, 0
	v_pk_mul_f32 v[44:45], v[44:45], v[164:165] op_sel:[0,1] op_sel_hi:[1,1]
	v_pk_mul_f32 v[46:47], v[46:47], v[164:165] op_sel:[0,1] op_sel_hi:[1,1]
	v_pk_mul_f32 v[40:41], v[40:41], v[164:165] op_sel:[0,1] op_sel_hi:[1,1]
	v_pk_mul_f32 v[42:43], v[42:43], v[164:165] op_sel:[0,1] op_sel_hi:[1,1]
	v_pk_mul_f32 v[36:37], v[36:37], v[164:165] op_sel:[0,1] op_sel_hi:[1,1]
	v_pk_mul_f32 v[38:39], v[38:39], v[164:165] op_sel:[0,1] op_sel_hi:[1,1]
	v_pk_mul_f32 v[32:33], v[32:33], v[164:165] op_sel:[0,1] op_sel_hi:[1,1]
	v_pk_mul_f32 v[34:35], v[34:35], v[164:165] op_sel:[0,1] op_sel_hi:[1,1]
	v_max_f32_e32 v44, 0, v44
	v_max_f32_e32 v45, 0, v45
	v_max_f32_e32 v46, 0, v46
	v_max_f32_e32 v47, 0, v47
	v_max_f32_e32 v40, 0, v40
	v_max_f32_e32 v41, 0, v41
	v_max_f32_e32 v42, 0, v42
	v_max_f32_e32 v43, 0, v43
	v_max_f32_e32 v36, 0, v36
	v_max_f32_e32 v37, 0, v37
	v_max_f32_e32 v38, 0, v38
	v_max_f32_e32 v39, 0, v39
	v_max_f32_e32 v32, 0, v32
	v_max_f32_e32 v33, 0, v33
	v_max_f32_e32 v34, 0, v34
	v_max_f32_e32 v35, 0, v35
	v_pk_mul_f32 v[44:45], v[44:45], v[44:45]
	v_pk_mul_f32 v[46:47], v[46:47], v[46:47]
	v_pk_mul_f32 v[40:41], v[40:41], v[40:41]
	v_pk_mul_f32 v[42:43], v[42:43], v[42:43]
	v_pk_mul_f32 v[36:37], v[36:37], v[36:37]
	v_pk_mul_f32 v[38:39], v[38:39], v[38:39]
	v_pk_mul_f32 v[32:33], v[32:33], v[32:33]
	v_pk_mul_f32 v[34:35], v[34:35], v[34:35]
	v_cvt_pk_bf16_f32 v44, v44, v45
	v_cvt_pk_bf16_f32 v45, v46, v47
	v_cvt_pk_bf16_f32 v46, v40, v41
	v_cvt_pk_bf16_f32 v47, v42, v43
	global_store_dwordx4 v138, v[44:47], s[100:101]
	v_cvt_pk_bf16_f32 v36, v36, v37
	v_cvt_pk_bf16_f32 v37, v38, v39
	v_cvt_pk_bf16_f32 v38, v32, v33
	v_cvt_pk_bf16_f32 v39, v34, v35
	global_store_dwordx4 v138, v[36:39], s[100:101] offset:256
	s_add_u32 s100, s100, 0x20000
	s_addc_u32 s101, s101, 0
	v_pk_mul_f32 v[28:29], v[28:29], v[166:167] op_sel_hi:[1,0]
	v_pk_mul_f32 v[30:31], v[30:31], v[166:167] op_sel_hi:[1,0]
	v_pk_mul_f32 v[24:25], v[24:25], v[166:167] op_sel_hi:[1,0]
	v_pk_mul_f32 v[26:27], v[26:27], v[166:167] op_sel_hi:[1,0]
	v_pk_mul_f32 v[20:21], v[20:21], v[166:167] op_sel_hi:[1,0]
	v_pk_mul_f32 v[22:23], v[22:23], v[166:167] op_sel_hi:[1,0]
	v_pk_mul_f32 v[16:17], v[16:17], v[166:167] op_sel_hi:[1,0]
	v_pk_mul_f32 v[18:19], v[18:19], v[166:167] op_sel_hi:[1,0]
	v_max_f32_e32 v28, 0, v28
	v_max_f32_e32 v29, 0, v29
	v_max_f32_e32 v30, 0, v30
	v_max_f32_e32 v31, 0, v31
	v_max_f32_e32 v24, 0, v24
	v_max_f32_e32 v25, 0, v25
	v_max_f32_e32 v26, 0, v26
	v_max_f32_e32 v27, 0, v27
	v_max_f32_e32 v20, 0, v20
	v_max_f32_e32 v21, 0, v21
	v_max_f32_e32 v22, 0, v22
	v_max_f32_e32 v23, 0, v23
	v_max_f32_e32 v16, 0, v16
	v_max_f32_e32 v17, 0, v17
	v_max_f32_e32 v18, 0, v18
	v_max_f32_e32 v19, 0, v19
	v_pk_mul_f32 v[28:29], v[28:29], v[28:29]
	v_pk_mul_f32 v[30:31], v[30:31], v[30:31]
	v_pk_mul_f32 v[24:25], v[24:25], v[24:25]
	v_pk_mul_f32 v[26:27], v[26:27], v[26:27]
	v_pk_mul_f32 v[20:21], v[20:21], v[20:21]
	v_pk_mul_f32 v[22:23], v[22:23], v[22:23]
	v_pk_mul_f32 v[16:17], v[16:17], v[16:17]
	v_pk_mul_f32 v[18:19], v[18:19], v[18:19]
	v_cvt_pk_bf16_f32 v28, v28, v29
	v_cvt_pk_bf16_f32 v29, v30, v31
	v_cvt_pk_bf16_f32 v30, v24, v25
	v_cvt_pk_bf16_f32 v31, v26, v27
	global_store_dwordx4 v138, v[28:31], s[100:101]
	v_cvt_pk_bf16_f32 v20, v20, v21
	v_cvt_pk_bf16_f32 v21, v22, v23
	v_cvt_pk_bf16_f32 v22, v16, v17
	v_cvt_pk_bf16_f32 v23, v18, v19
	global_store_dwordx4 v138, v[20:23], s[100:101] offset:256
	s_add_u32 s100, s100, 0x20000
	s_addc_u32 s101, s101, 0
	v_pk_mul_f32 v[12:13], v[12:13], v[166:167] op_sel:[0,1] op_sel_hi:[1,1]
	v_pk_mul_f32 v[14:15], v[14:15], v[166:167] op_sel:[0,1] op_sel_hi:[1,1]
	v_pk_mul_f32 v[8:9], v[8:9], v[166:167] op_sel:[0,1] op_sel_hi:[1,1]
	v_pk_mul_f32 v[10:11], v[10:11], v[166:167] op_sel:[0,1] op_sel_hi:[1,1]
	v_pk_mul_f32 v[4:5], v[4:5], v[166:167] op_sel:[0,1] op_sel_hi:[1,1]
	v_pk_mul_f32 v[6:7], v[6:7], v[166:167] op_sel:[0,1] op_sel_hi:[1,1]
	v_pk_mul_f32 v[0:1], v[0:1], v[166:167] op_sel:[0,1] op_sel_hi:[1,1]
	v_pk_mul_f32 v[2:3], v[2:3], v[166:167] op_sel:[0,1] op_sel_hi:[1,1]
	v_max_f32_e32 v12, 0, v12
	v_max_f32_e32 v13, 0, v13
	v_max_f32_e32 v14, 0, v14
	v_max_f32_e32 v15, 0, v15
	v_max_f32_e32 v8, 0, v8
	v_max_f32_e32 v9, 0, v9
	v_max_f32_e32 v10, 0, v10
	v_max_f32_e32 v11, 0, v11
	v_max_f32_e32 v4, 0, v4
	v_max_f32_e32 v5, 0, v5
	v_max_f32_e32 v6, 0, v6
	v_max_f32_e32 v7, 0, v7
	v_max_f32_e32 v0, 0, v0
	v_max_f32_e32 v1, 0, v1
	v_max_f32_e32 v2, 0, v2
	v_max_f32_e32 v3, 0, v3
	v_pk_mul_f32 v[12:13], v[12:13], v[12:13]
	v_pk_mul_f32 v[14:15], v[14:15], v[14:15]
	v_pk_mul_f32 v[8:9], v[8:9], v[8:9]
	v_pk_mul_f32 v[10:11], v[10:11], v[10:11]
	v_pk_mul_f32 v[4:5], v[4:5], v[4:5]
	v_pk_mul_f32 v[6:7], v[6:7], v[6:7]
	v_pk_mul_f32 v[0:1], v[0:1], v[0:1]
	v_pk_mul_f32 v[2:3], v[2:3], v[2:3]
	v_cvt_pk_bf16_f32 v12, v12, v13
	v_cvt_pk_bf16_f32 v13, v14, v15
	v_cvt_pk_bf16_f32 v14, v8, v9
	v_cvt_pk_bf16_f32 v15, v10, v11
	global_store_dwordx4 v138, v[12:15], s[100:101]
	v_cvt_pk_bf16_f32 v4, v4, v5
	v_cvt_pk_bf16_f32 v5, v6, v7
	v_cvt_pk_bf16_f32 v6, v0, v1
	v_cvt_pk_bf16_f32 v7, v2, v3
	global_store_dwordx4 v138, v[4:7], s[100:101] offset:256
	s_andn2_b64 vcc, exec, s[4:5]
	s_cbranch_vccnz .LBB0_787
	s_andn2_b64 vcc, exec, s[0:1]
	s_cbranch_vccnz .LBB0_786
	s_barrier
	s_branch .LBB0_786
.LBB0_801:
	s_barrier
.LBB0_802:
	v_readlane_b32 s0, v252, 50
	v_mov_b32_e32 v0, v226
	v_readlane_b32 s1, v252, 51
	s_and_b64 vcc, exec, s[0:1]
	v_readfirstlane_b32 s0, v0
	s_cbranch_vccnz .LBB0_811
	s_ashr_i32 s4, s0, 6
	s_ashr_i32 s0, s0, 2
	s_andn2_b32 s0, s0, 63
	v_bfe_u32 v176, v0, 3, 3
	s_mul_i32 s1, s4, 0x2400
	v_or_b32_e32 v177, s0, v176
	s_lshl_b32 s0, s4, 9
	s_add_i32 s5, s1, 0
	s_and_b32 s6, s0, 0x600
	s_add_u32 s0, s46, s6
	v_lshlrev_b32_e32 v2, 4, v0
	s_addc_u32 s1, s47, 0
	v_and_b32_e32 v208, 0x70, v2
	v_lshl_add_u64 v[160:161], s[0:1], 0, v[208:209]
	s_add_u32 s0, s26, s6
	s_addc_u32 s1, s27, 0
	v_and_b32_e32 v1, 15, v0
	v_lshl_add_u64 v[162:163], s[0:1], 0, v[208:209]
	v_mov_b32_e32 v3, s5
	s_movk_i32 s0, 0x90
	v_and_b32_e32 v2, 48, v0
	v_mad_u32_u24 v4, v176, s0, v3
	v_mad_u32_u24 v3, v1, s0, v3
	s_lshl_b32 s0, s4, 13
	v_ashrrev_i32_e32 v178, 2, v0
	v_lshlrev_b32_e32 v7, 2, v0
	v_ashrrev_i32_e32 v0, 6, v0
	s_add_i32 s5, s5, s0
	v_and_b32_e32 v164, 12, v7
	v_and_b32_e32 v7, 0x3ffffc, v0
	v_or_b32_e32 v0, 3, v0
	s_movk_i32 s0, 0x4400
	v_mul_lo_u32 v0, v0, s0
	v_readlane_b32 s0, v252, 47
	s_add_u32 s0, s0, s6
	v_readlane_b32 s12, v253, 0
	s_addc_u32 s1, 0, 0
	v_readlane_b32 s14, v253, 2
	v_and_b32_e32 v6, 63, v178
	v_readlane_b32 s15, v253, 3
	s_add_u32 s0, s14, s0
	v_mul_u32_u24_e32 v6, 0x110, v6
	v_lshlrev_b32_e32 v8, 2, v164
	s_addc_u32 s1, s15, s1
	v_add_u32_e32 v5, s5, v2
	v_add3_u32 v6, 0, v6, v8
	v_mul_u32_u24_e32 v7, 0x4400, v7
	v_mul_u32_u24_e32 v1, 0x110, v1
	s_add_u32 s4, s14, s6
	v_mov_b32_e32 v165, v209
	v_or_b32_e32 v179, 48, v176
	v_or_b32_e32 v180, 32, v176
	s_addc_u32 s5, s15, 0
	v_add_u32_e32 v181, v5, v1
	v_add_u32_e32 v182, v6, v7
	v_add_u32_e32 v183, v6, v0
	v_add_u32_e32 v184, v4, v208
	v_add_u32_e32 v185, v3, v2
	s_mov_b32 s16, s2
	v_readlane_b32 s13, v253, 1
	s_branch .LBB0_805

.LBB0_872:
	v_xor_b32_e32 v140, 16, v230
	v_xor_b32_e32 v141, 32, v230
	v_lshlrev_b32_e32 v140, 2, v140
	v_lshlrev_b32_e32 v141, 2, v141
	s_mov_b64 s[100:101], s[46:47]
	s_waitcnt vmcnt(14)
	v_lshlrev_b32_e32 v142, 16, v148
	v_and_b32_e32 v143, 0xffff0000, v148
	v_pk_add_f32 v[124:125], v[124:125], v[142:143]
	v_pk_mul_f32 v[222:223], v[124:125], v[124:125]
	v_cvt_pk_bf16_f32 v148, v124, v125
	v_lshlrev_b32_e32 v142, 16, v149
	v_and_b32_e32 v143, 0xffff0000, v149
	v_pk_add_f32 v[126:127], v[126:127], v[142:143]
	v_pk_fma_f32 v[222:223], v[126:127], v[126:127], v[222:223]
	v_cvt_pk_bf16_f32 v149, v126, v127
	v_lshlrev_b32_e32 v142, 16, v150
	v_and_b32_e32 v143, 0xffff0000, v150
	v_pk_add_f32 v[120:121], v[120:121], v[142:143]
	v_pk_fma_f32 v[222:223], v[120:121], v[120:121], v[222:223]
	v_cvt_pk_bf16_f32 v150, v120, v121
	v_lshlrev_b32_e32 v142, 16, v151
	v_and_b32_e32 v143, 0xffff0000, v151
	v_pk_add_f32 v[122:123], v[122:123], v[142:143]
	v_pk_fma_f32 v[222:223], v[122:123], v[122:123], v[222:223]
	v_cvt_pk_bf16_f32 v151, v122, v123
	global_store_dwordx4 v138, v[148:151], s[100:101]
	v_lshlrev_b32_e32 v142, 16, v152
	v_and_b32_e32 v143, 0xffff0000, v152
	v_pk_add_f32 v[116:117], v[116:117], v[142:143]
	v_pk_fma_f32 v[222:223], v[116:117], v[116:117], v[222:223]
	v_cvt_pk_bf16_f32 v152, v116, v117
	v_lshlrev_b32_e32 v142, 16, v153
	v_and_b32_e32 v143, 0xffff0000, v153
	v_pk_add_f32 v[118:119], v[118:119], v[142:143]
	v_pk_fma_f32 v[222:223], v[118:119], v[118:119], v[222:223]
	v_cvt_pk_bf16_f32 v153, v118, v119
	v_lshlrev_b32_e32 v142, 16, v154
	v_and_b32_e32 v143, 0xffff0000, v154
	v_pk_add_f32 v[112:113], v[112:113], v[142:143]
	v_pk_fma_f32 v[222:223], v[112:113], v[112:113], v[222:223]
	v_cvt_pk_bf16_f32 v154, v112, v113
	v_lshlrev_b32_e32 v142, 16, v155
	v_and_b32_e32 v143, 0xffff0000, v155
	v_pk_add_f32 v[114:115], v[114:115], v[142:143]
	v_pk_fma_f32 v[222:223], v[114:115], v[114:115], v[222:223]
	v_cvt_pk_bf16_f32 v155, v114, v115
	global_store_dwordx4 v138, v[152:155], s[100:101] offset:256
	v_add_f32_e32 v124, v222, v223
	s_add_u32 s100, s100, 0x8000
	s_addc_u32 s101, s101, 0
	s_waitcnt vmcnt(14)
	v_lshlrev_b32_e32 v142, 16, v156
	v_and_b32_e32 v143, 0xffff0000, v156
	v_pk_add_f32 v[108:109], v[108:109], v[142:143]
	v_pk_mul_f32 v[222:223], v[108:109], v[108:109]
	v_cvt_pk_bf16_f32 v156, v108, v109
	v_lshlrev_b32_e32 v142, 16, v157
	v_and_b32_e32 v143, 0xffff0000, v157
	v_pk_add_f32 v[110:111], v[110:111], v[142:143]
	v_pk_fma_f32 v[222:223], v[110:111], v[110:111], v[222:223]
	v_cvt_pk_bf16_f32 v157, v110, v111
	v_lshlrev_b32_e32 v142, 16, v158
	v_and_b32_e32 v143, 0xffff0000, v158
	v_pk_add_f32 v[104:105], v[104:105], v[142:143]
	v_pk_fma_f32 v[222:223], v[104:105], v[104:105], v[222:223]
	v_cvt_pk_bf16_f32 v158, v104, v105
	v_lshlrev_b32_e32 v142, 16, v159
	v_and_b32_e32 v143, 0xffff0000, v159
	v_pk_add_f32 v[106:107], v[106:107], v[142:143]
	v_pk_fma_f32 v[222:223], v[106:107], v[106:107], v[222:223]
	v_cvt_pk_bf16_f32 v159, v106, v107
	global_store_dwordx4 v138, v[156:159], s[100:101]
	v_lshlrev_b32_e32 v142, 16, v160
	v_and_b32_e32 v143, 0xffff0000, v160
	v_pk_add_f32 v[100:101], v[100:101], v[142:143]
	v_pk_fma_f32 v[222:223], v[100:101], v[100:101], v[222:223]
	v_cvt_pk_bf16_f32 v160, v100, v101
	v_lshlrev_b32_e32 v142, 16, v161
	v_and_b32_e32 v143, 0xffff0000, v161
	v_pk_add_f32 v[102:103], v[102:103], v[142:143]
	v_pk_fma_f32 v[222:223], v[102:103], v[102:103], v[222:223]
	v_cvt_pk_bf16_f32 v161, v102, v103
	v_lshlrev_b32_e32 v142, 16, v162
	v_and_b32_e32 v143, 0xffff0000, v162
	v_pk_add_f32 v[96:97], v[96:97], v[142:143]
	v_pk_fma_f32 v[222:223], v[96:97], v[96:97], v[222:223]
	v_cvt_pk_bf16_f32 v162, v96, v97
	v_lshlrev_b32_e32 v142, 16, v163
	v_and_b32_e32 v143, 0xffff0000, v163
	v_pk_add_f32 v[98:99], v[98:99], v[142:143]
	v_pk_fma_f32 v[222:223], v[98:99], v[98:99], v[222:223]
	v_cvt_pk_bf16_f32 v163, v98, v99
	global_store_dwordx4 v138, v[160:163], s[100:101] offset:256
	v_add_f32_e32 v108, v222, v223
	s_add_u32 s100, s100, 0x8000
	s_addc_u32 s101, s101, 0
	s_waitcnt vmcnt(14)
	v_lshlrev_b32_e32 v142, 16, v164
	v_and_b32_e32 v143, 0xffff0000, v164
	v_pk_add_f32 v[92:93], v[92:93], v[142:143]
	v_pk_mul_f32 v[222:223], v[92:93], v[92:93]
	v_cvt_pk_bf16_f32 v164, v92, v93
	v_lshlrev_b32_e32 v142, 16, v165
	v_and_b32_e32 v143, 0xffff0000, v165
	v_pk_add_f32 v[94:95], v[94:95], v[142:143]
	v_pk_fma_f32 v[222:223], v[94:95], v[94:95], v[222:223]
	v_cvt_pk_bf16_f32 v165, v94, v95
	v_lshlrev_b32_e32 v142, 16, v166
	v_and_b32_e32 v143, 0xffff0000, v166
	v_pk_add_f32 v[88:89], v[88:89], v[142:143]
	v_pk_fma_f32 v[222:223], v[88:89], v[88:89], v[222:223]
	v_cvt_pk_bf16_f32 v166, v88, v89
	v_lshlrev_b32_e32 v142, 16, v167
	v_and_b32_e32 v143, 0xffff0000, v167
	v_pk_add_f32 v[90:91], v[90:91], v[142:143]
	v_pk_fma_f32 v[222:223], v[90:91], v[90:91], v[222:223]
	v_cvt_pk_bf16_f32 v167, v90, v91
	global_store_dwordx4 v138, v[164:167], s[100:101]
	v_lshlrev_b32_e32 v142, 16, v168
	v_and_b32_e32 v143, 0xffff0000, v168
	v_pk_add_f32 v[84:85], v[84:85], v[142:143]
	v_pk_fma_f32 v[222:223], v[84:85], v[84:85], v[222:223]
	v_cvt_pk_bf16_f32 v168, v84, v85
	v_lshlrev_b32_e32 v142, 16, v169
	v_and_b32_e32 v143, 0xffff0000, v169
	v_pk_add_f32 v[86:87], v[86:87], v[142:143]
	v_pk_fma_f32 v[222:223], v[86:87], v[86:87], v[222:223]
	v_cvt_pk_bf16_f32 v169, v86, v87
	v_lshlrev_b32_e32 v142, 16, v170
	v_and_b32_e32 v143, 0xffff0000, v170
	v_pk_add_f32 v[80:81], v[80:81], v[142:143]
	v_pk_fma_f32 v[222:223], v[80:81], v[80:81], v[222:223]
	v_cvt_pk_bf16_f32 v170, v80, v81
	v_lshlrev_b32_e32 v142, 16, v171
	v_and_b32_e32 v143, 0xffff0000, v171
	v_pk_add_f32 v[82:83], v[82:83], v[142:143]
	v_pk_fma_f32 v[222:223], v[82:83], v[82:83], v[222:223]
	v_cvt_pk_bf16_f32 v171, v82, v83
	global_store_dwordx4 v138, v[168:171], s[100:101] offset:256
	v_add_f32_e32 v92, v222, v223
	s_add_u32 s100, s100, 0x8000
	s_addc_u32 s101, s101, 0
	s_waitcnt vmcnt(14)
	v_lshlrev_b32_e32 v142, 16, v172
	v_and_b32_e32 v143, 0xffff0000, v172
	v_pk_add_f32 v[76:77], v[76:77], v[142:143]
	v_pk_mul_f32 v[222:223], v[76:77], v[76:77]
	v_cvt_pk_bf16_f32 v172, v76, v77
	v_lshlrev_b32_e32 v142, 16, v173
	v_and_b32_e32 v143, 0xffff0000, v173
	v_pk_add_f32 v[78:79], v[78:79], v[142:143]
	v_pk_fma_f32 v[222:223], v[78:79], v[78:79], v[222:223]
	v_cvt_pk_bf16_f32 v173, v78, v79
	v_lshlrev_b32_e32 v142, 16, v174
	v_and_b32_e32 v143, 0xffff0000, v174
	v_pk_add_f32 v[72:73], v[72:73], v[142:143]
	v_pk_fma_f32 v[222:223], v[72:73], v[72:73], v[222:223]
	v_cvt_pk_bf16_f32 v174, v72, v73
	v_lshlrev_b32_e32 v142, 16, v175
	v_and_b32_e32 v143, 0xffff0000, v175
	v_pk_add_f32 v[74:75], v[74:75], v[142:143]
	v_pk_fma_f32 v[222:223], v[74:75], v[74:75], v[222:223]
	v_cvt_pk_bf16_f32 v175, v74, v75
	global_store_dwordx4 v138, v[172:175], s[100:101]
	v_lshlrev_b32_e32 v142, 16, v176
	v_and_b32_e32 v143, 0xffff0000, v176
	v_pk_add_f32 v[68:69], v[68:69], v[142:143]
	v_pk_fma_f32 v[222:223], v[68:69], v[68:69], v[222:223]
	v_cvt_pk_bf16_f32 v176, v68, v69
	v_lshlrev_b32_e32 v142, 16, v177
	v_and_b32_e32 v143, 0xffff0000, v177
	v_pk_add_f32 v[70:71], v[70:71], v[142:143]
	v_pk_fma_f32 v[222:223], v[70:71], v[70:71], v[222:223]
	v_cvt_pk_bf16_f32 v177, v70, v71
	v_lshlrev_b32_e32 v142, 16, v178
	v_and_b32_e32 v143, 0xffff0000, v178
	v_pk_add_f32 v[64:65], v[64:65], v[142:143]
	v_pk_fma_f32 v[222:223], v[64:65], v[64:65], v[222:223]
	v_cvt_pk_bf16_f32 v178, v64, v65
	v_lshlrev_b32_e32 v142, 16, v179
	v_and_b32_e32 v143, 0xffff0000, v179
	v_pk_add_f32 v[66:67], v[66:67], v[142:143]
	v_pk_fma_f32 v[222:223], v[66:67], v[66:67], v[222:223]
	v_cvt_pk_bf16_f32 v179, v66, v67
	global_store_dwordx4 v138, v[176:179], s[100:101] offset:256
	v_add_f32_e32 v76, v222, v223
	s_add_u32 s100, s100, 0x28000
	s_addc_u32 s101, s101, 0
	s_waitcnt vmcnt(14)
	v_lshlrev_b32_e32 v142, 16, v180
	v_and_b32_e32 v143, 0xffff0000, v180
	v_pk_add_f32 v[60:61], v[60:61], v[142:143]
	v_pk_mul_f32 v[222:223], v[60:61], v[60:61]
	v_cvt_pk_bf16_f32 v180, v60, v61
	v_lshlrev_b32_e32 v142, 16, v181
	v_and_b32_e32 v143, 0xffff0000, v181
	v_pk_add_f32 v[62:63], v[62:63], v[142:143]
	v_pk_fma_f32 v[222:223], v[62:63], v[62:63], v[222:223]
	v_cvt_pk_bf16_f32 v181, v62, v63
	v_lshlrev_b32_e32 v142, 16, v182
	v_and_b32_e32 v143, 0xffff0000, v182
	v_pk_add_f32 v[56:57], v[56:57], v[142:143]
	v_pk_fma_f32 v[222:223], v[56:57], v[56:57], v[222:223]
	v_cvt_pk_bf16_f32 v182, v56, v57
	v_lshlrev_b32_e32 v142, 16, v183
	v_and_b32_e32 v143, 0xffff0000, v183
	v_pk_add_f32 v[58:59], v[58:59], v[142:143]
	v_pk_fma_f32 v[222:223], v[58:59], v[58:59], v[222:223]
	v_cvt_pk_bf16_f32 v183, v58, v59
	global_store_dwordx4 v138, v[180:183], s[100:101]
	v_lshlrev_b32_e32 v142, 16, v184
	v_and_b32_e32 v143, 0xffff0000, v184
	v_pk_add_f32 v[52:53], v[52:53], v[142:143]
	v_pk_fma_f32 v[222:223], v[52:53], v[52:53], v[222:223]
	v_cvt_pk_bf16_f32 v184, v52, v53
	v_lshlrev_b32_e32 v142, 16, v185
	v_and_b32_e32 v143, 0xffff0000, v185
	v_pk_add_f32 v[54:55], v[54:55], v[142:143]
	v_pk_fma_f32 v[222:223], v[54:55], v[54:55], v[222:223]
	v_cvt_pk_bf16_f32 v185, v54, v55
	v_lshlrev_b32_e32 v142, 16, v186
	v_and_b32_e32 v143, 0xffff0000, v186
	v_pk_add_f32 v[48:49], v[48:49], v[142:143]
	v_pk_fma_f32 v[222:223], v[48:49], v[48:49], v[222:223]
	v_cvt_pk_bf16_f32 v186, v48, v49
	v_lshlrev_b32_e32 v142, 16, v187
	v_and_b32_e32 v143, 0xffff0000, v187
	v_pk_add_f32 v[50:51], v[50:51], v[142:143]
	v_pk_fma_f32 v[222:223], v[50:51], v[50:51], v[222:223]
	v_cvt_pk_bf16_f32 v187, v50, v51
	global_store_dwordx4 v138, v[184:187], s[100:101] offset:256
	v_add_f32_e32 v60, v222, v223
	s_add_u32 s100, s100, 0x8000
	s_addc_u32 s101, s101, 0
	s_waitcnt vmcnt(14)
	v_lshlrev_b32_e32 v142, 16, v188
	v_and_b32_e32 v143, 0xffff0000, v188
	v_pk_add_f32 v[44:45], v[44:45], v[142:143]
	v_pk_mul_f32 v[222:223], v[44:45], v[44:45]
	v_cvt_pk_bf16_f32 v188, v44, v45
	v_lshlrev_b32_e32 v142, 16, v189
	v_and_b32_e32 v143, 0xffff0000, v189
	v_pk_add_f32 v[46:47], v[46:47], v[142:143]
	v_pk_fma_f32 v[222:223], v[46:47], v[46:47], v[222:223]
	v_cvt_pk_bf16_f32 v189, v46, v47
	v_lshlrev_b32_e32 v142, 16, v190
	v_and_b32_e32 v143, 0xffff0000, v190
	v_pk_add_f32 v[40:41], v[40:41], v[142:143]
	v_pk_fma_f32 v[222:223], v[40:41], v[40:41], v[222:223]
	v_cvt_pk_bf16_f32 v190, v40, v41
	v_lshlrev_b32_e32 v142, 16, v191
	v_and_b32_e32 v143, 0xffff0000, v191
	v_pk_add_f32 v[42:43], v[42:43], v[142:143]
	v_pk_fma_f32 v[222:223], v[42:43], v[42:43], v[222:223]
	v_cvt_pk_bf16_f32 v191, v42, v43
	global_store_dwordx4 v138, v[188:191], s[100:101]
	v_lshlrev_b32_e32 v142, 16, v192
	v_and_b32_e32 v143, 0xffff0000, v192
	v_pk_add_f32 v[36:37], v[36:37], v[142:143]
	v_pk_fma_f32 v[222:223], v[36:37], v[36:37], v[222:223]
	v_cvt_pk_bf16_f32 v192, v36, v37
	v_lshlrev_b32_e32 v142, 16, v193
	v_and_b32_e32 v143, 0xffff0000, v193
	v_pk_add_f32 v[38:39], v[38:39], v[142:143]
	v_pk_fma_f32 v[222:223], v[38:39], v[38:39], v[222:223]
	v_cvt_pk_bf16_f32 v193, v38, v39
	v_lshlrev_b32_e32 v142, 16, v194
	v_and_b32_e32 v143, 0xffff0000, v194
	v_pk_add_f32 v[32:33], v[32:33], v[142:143]
	v_pk_fma_f32 v[222:223], v[32:33], v[32:33], v[222:223]
	v_cvt_pk_bf16_f32 v194, v32, v33
	v_lshlrev_b32_e32 v142, 16, v195
	v_and_b32_e32 v143, 0xffff0000, v195
	v_pk_add_f32 v[34:35], v[34:35], v[142:143]
	v_pk_fma_f32 v[222:223], v[34:35], v[34:35], v[222:223]
	v_cvt_pk_bf16_f32 v195, v34, v35
	global_store_dwordx4 v138, v[192:195], s[100:101] offset:256
	v_add_f32_e32 v44, v222, v223
	s_add_u32 s100, s100, 0x8000
	s_addc_u32 s101, s101, 0
	s_waitcnt vmcnt(14)
	v_lshlrev_b32_e32 v142, 16, v196
	v_and_b32_e32 v143, 0xffff0000, v196
	v_pk_add_f32 v[28:29], v[28:29], v[142:143]
	v_pk_mul_f32 v[222:223], v[28:29], v[28:29]
	v_cvt_pk_bf16_f32 v196, v28, v29
	v_lshlrev_b32_e32 v142, 16, v197
	v_and_b32_e32 v143, 0xffff0000, v197
	v_pk_add_f32 v[30:31], v[30:31], v[142:143]
	v_pk_fma_f32 v[222:223], v[30:31], v[30:31], v[222:223]
	v_cvt_pk_bf16_f32 v197, v30, v31
	v_lshlrev_b32_e32 v142, 16, v198
	v_and_b32_e32 v143, 0xffff0000, v198
	v_pk_add_f32 v[24:25], v[24:25], v[142:143]
	v_pk_fma_f32 v[222:223], v[24:25], v[24:25], v[222:223]
	v_cvt_pk_bf16_f32 v198, v24, v25
	v_lshlrev_b32_e32 v142, 16, v199
	v_and_b32_e32 v143, 0xffff0000, v199
	v_pk_add_f32 v[26:27], v[26:27], v[142:143]
	v_pk_fma_f32 v[222:223], v[26:27], v[26:27], v[222:223]
	v_cvt_pk_bf16_f32 v199, v26, v27
	global_store_dwordx4 v138, v[196:199], s[100:101]
	v_lshlrev_b32_e32 v142, 16, v200
	v_and_b32_e32 v143, 0xffff0000, v200
	v_pk_add_f32 v[20:21], v[20:21], v[142:143]
	v_pk_fma_f32 v[222:223], v[20:21], v[20:21], v[222:223]
	v_cvt_pk_bf16_f32 v200, v20, v21
	v_lshlrev_b32_e32 v142, 16, v201
	v_and_b32_e32 v143, 0xffff0000, v201
	v_pk_add_f32 v[22:23], v[22:23], v[142:143]
	v_pk_fma_f32 v[222:223], v[22:23], v[22:23], v[222:223]
	v_cvt_pk_bf16_f32 v201, v22, v23
	v_lshlrev_b32_e32 v142, 16, v202
	v_and_b32_e32 v143, 0xffff0000, v202
	v_pk_add_f32 v[16:17], v[16:17], v[142:143]
	v_pk_fma_f32 v[222:223], v[16:17], v[16:17], v[222:223]
	v_cvt_pk_bf16_f32 v202, v16, v17
	v_lshlrev_b32_e32 v142, 16, v203
	v_and_b32_e32 v143, 0xffff0000, v203
	v_pk_add_f32 v[18:19], v[18:19], v[142:143]
	v_pk_fma_f32 v[222:223], v[18:19], v[18:19], v[222:223]
	v_cvt_pk_bf16_f32 v203, v18, v19
	global_store_dwordx4 v138, v[200:203], s[100:101] offset:256
	v_add_f32_e32 v28, v222, v223
	s_add_u32 s100, s100, 0x8000
	s_addc_u32 s101, s101, 0
	s_waitcnt vmcnt(14)
	v_lshlrev_b32_e32 v142, 16, v204
	v_and_b32_e32 v143, 0xffff0000, v204
	v_pk_add_f32 v[12:13], v[12:13], v[142:143]
	v_pk_mul_f32 v[222:223], v[12:13], v[12:13]
	v_cvt_pk_bf16_f32 v204, v12, v13
	v_lshlrev_b32_e32 v142, 16, v205
	v_and_b32_e32 v143, 0xffff0000, v205
	v_pk_add_f32 v[14:15], v[14:15], v[142:143]
	v_pk_fma_f32 v[222:223], v[14:15], v[14:15], v[222:223]
	v_cvt_pk_bf16_f32 v205, v14, v15
	v_lshlrev_b32_e32 v142, 16, v206
	v_and_b32_e32 v143, 0xffff0000, v206
	v_pk_add_f32 v[8:9], v[8:9], v[142:143]
	v_pk_fma_f32 v[222:223], v[8:9], v[8:9], v[222:223]
	v_cvt_pk_bf16_f32 v206, v8, v9
	v_lshlrev_b32_e32 v142, 16, v207
	v_and_b32_e32 v143, 0xffff0000, v207
	v_pk_add_f32 v[10:11], v[10:11], v[142:143]
	v_pk_fma_f32 v[222:223], v[10:11], v[10:11], v[222:223]
	v_cvt_pk_bf16_f32 v207, v10, v11
	global_store_dwordx4 v138, v[204:207], s[100:101]
	v_lshlrev_b32_e32 v142, 16, v236
	v_and_b32_e32 v143, 0xffff0000, v236
	v_pk_add_f32 v[4:5], v[4:5], v[142:143]
	v_pk_fma_f32 v[222:223], v[4:5], v[4:5], v[222:223]
	v_cvt_pk_bf16_f32 v236, v4, v5
	v_lshlrev_b32_e32 v142, 16, v237
	v_and_b32_e32 v143, 0xffff0000, v237
	v_pk_add_f32 v[6:7], v[6:7], v[142:143]
	v_pk_fma_f32 v[222:223], v[6:7], v[6:7], v[222:223]
	v_cvt_pk_bf16_f32 v237, v6, v7
	v_lshlrev_b32_e32 v142, 16, v238
	v_and_b32_e32 v143, 0xffff0000, v238
	v_pk_add_f32 v[0:1], v[0:1], v[142:143]
	v_pk_fma_f32 v[222:223], v[0:1], v[0:1], v[222:223]
	v_cvt_pk_bf16_f32 v238, v0, v1
	v_lshlrev_b32_e32 v142, 16, v239
	v_and_b32_e32 v143, 0xffff0000, v239
	v_pk_add_f32 v[2:3], v[2:3], v[142:143]
	v_pk_fma_f32 v[222:223], v[2:3], v[2:3], v[222:223]
	v_cvt_pk_bf16_f32 v239, v2, v3
	global_store_dwordx4 v138, v[236:239], s[100:101] offset:256
	v_add_f32_e32 v12, v222, v223
	ds_bpermute_b32 v125, v140, v124
	ds_bpermute_b32 v109, v140, v108
	ds_bpermute_b32 v93, v140, v92
	ds_bpermute_b32 v77, v140, v76
	ds_bpermute_b32 v61, v140, v60
	ds_bpermute_b32 v45, v140, v44
	ds_bpermute_b32 v29, v140, v28
	ds_bpermute_b32 v13, v140, v12
	s_waitcnt lgkmcnt(0)
	v_add_f32_e32 v124, v124, v125
	v_add_f32_e32 v108, v108, v109
	v_add_f32_e32 v92, v92, v93
	v_add_f32_e32 v76, v76, v77
	v_add_f32_e32 v60, v60, v61
	v_add_f32_e32 v44, v44, v45
	v_add_f32_e32 v28, v28, v29
	v_add_f32_e32 v12, v12, v13
	ds_bpermute_b32 v125, v141, v124
	ds_bpermute_b32 v109, v141, v108
	ds_bpermute_b32 v93, v141, v92
	ds_bpermute_b32 v77, v141, v76
	ds_bpermute_b32 v61, v141, v60
	ds_bpermute_b32 v45, v141, v44
	ds_bpermute_b32 v29, v141, v28
	ds_bpermute_b32 v13, v141, v12
	s_waitcnt lgkmcnt(0)
	v_add_f32_e32 v124, v124, v125
	v_add_f32_e32 v108, v108, v109
	v_add_f32_e32 v92, v92, v93
	v_add_f32_e32 v76, v76, v77
	v_add_f32_e32 v60, v60, v61
	v_add_f32_e32 v44, v44, v45
	v_add_f32_e32 v28, v28, v29
	v_add_f32_e32 v12, v12, v13
	s_and_saveexec_b64 s[98:99], s[4:5]
	global_atomic_add_f32 v139, v124, s[12:13]
	global_atomic_add_f32 v139, v108, s[12:13] offset:64
	global_atomic_add_f32 v139, v92, s[12:13] offset:128
	global_atomic_add_f32 v139, v76, s[12:13] offset:192
	global_atomic_add_f32 v139, v60, s[12:13] offset:512
	global_atomic_add_f32 v139, v44, s[12:13] offset:576
	global_atomic_add_f32 v139, v28, s[12:13] offset:640
	global_atomic_add_f32 v139, v12, s[12:13] offset:704
	s_or_b64 exec, exec, s[98:99]
	v_readlane_b32 s76, v252, 46
	s_mov_b32 s77, 0x20000
	s_mov_b32 s28, 0x30000
	s_mov_b32 s29, 0x40000
	s_mov_b32 s72, 0x50000
	s_andn2_b64 vcc, exec, s[6:7]
	s_mov_b64 s[6:7], -1
	s_cbranch_vccnz .LBB0_861
	s_andn2_b64 vcc, exec, s[0:1]
	s_cbranch_vccnz .LBB0_860
	s_barrier
	s_branch .LBB0_860
.LBB0_891:
	s_barrier
.LBB0_892:
	v_readlane_b32 s0, v252, 50
	v_mov_b32_e32 v0, v226
	v_readlane_b32 s1, v252, 51
	s_and_b64 vcc, exec, s[0:1]
	v_readfirstlane_b32 s0, v0
	s_cbranch_vccnz .LBB0_903
	s_ashr_i32 s0, s0, 6
	s_mul_i32 s1, s0, 0x2400
	s_lshl_b32 s0, s0, 9
	s_add_i32 s6, s1, 0
	s_ashr_i32 s1, s0, 31
	s_lshl_b64 s[4:5], s[0:1], 1
	v_and_b32_e32 v2, 7, v0
	s_add_u32 s0, s88, s4
	s_addc_u32 s1, s89, s5
	v_lshlrev_b32_e32 v208, 4, v2
	v_lshl_add_u64 v[176:177], s[0:1], 0, v[208:209]
	s_add_u32 s0, s30, s4
	s_addc_u32 s1, s8, s5
	s_waitcnt lgkmcnt(0)
	v_and_b32_e32 v1, 15, v0
	v_bfe_u32 v194, v0, 3, 3
	v_lshl_add_u64 v[178:179], s[0:1], 0, v[208:209]
	v_and_b32_e32 v4, 48, v0
	v_mov_b32_e32 v5, s6
	s_movk_i32 s0, 0x90
	v_readlane_b32 s16, v253, 0
	v_mul_u32_u24_e32 v3, 0x90, v1
	v_mad_u32_u24 v6, v194, s0, v5
	v_mad_u32_u24 v1, v1, s0, v5
	v_add_u32_e32 v5, s6, v4
	v_readlane_b32 s18, v253, 2
	v_readlane_b32 s6, v252, 47
	v_ashrrev_i32_e32 v195, 3, v0
	v_readlane_b32 s19, v253, 3
	s_add_u32 s6, s18, s6
	v_lshlrev_b32_e32 v0, 2, v2
	v_mul_lo_u32 v7, v195, s0
	s_addc_u32 s7, s19, 0
	v_add3_u32 v196, 0, v7, v208
	v_cmp_eq_u32_e64 s[0:1], 0, v2
	v_lshl_add_u64 v[180:181], s[6:7], 0, v[208:209]
	v_lshlrev_b32_e32 v197, 12, v194
	v_lshl_add_u64 v[182:183], s[18:19], 0, v[208:209]
	v_or_b32_e32 v198, 0x4000, v194
	v_add_u32_e32 v199, v5, v3
	v_lshlrev_b32_e32 v184, 1, v0
	v_add_u32_e32 v200, v6, v208
	v_add_u32_e32 v201, v1, v4
	v_readlane_b32 s8, v252, 41
	v_readlane_b32 s10, v252, 43
	s_mov_b32 s11, s2
	v_readlane_b32 s17, v253, 1
	s_branch .LBB0_895
